# adds: 64-byte alignment of each pre-MFMA setprio+barrier (MFMA segment starts 8 bytes into a cache line)
# baseline (speedup 1.0000x reference)
.LBB0_126:
	ds_read_b128 v[130:133], v176
	ds_read_b128 v[134:137], v176 offset:1024
	ds_read_b128 v[170:173], v176 offset:2048
	ds_read_b128 v[180:183], v176 offset:3072
	ds_read_b128 v[184:187], v177
	ds_read_b128 v[188:191], v177 offset:1024
	ds_read_b128 v[192:195], v177 offset:2048
	ds_read_b128 v[198:201], v177 offset:3072
	s_add_u32 s14, s8, 0xfff00080
	s_addc_u32 s15, s9, -1
	s_cmp_eq_u32 s29, 60
	s_cselect_b32 s19, s11, s15
	s_cselect_b32 s18, s13, s14
	s_cselect_b32 s15, s17, s28
	s_cselect_b32 s14, s20, s21
	s_add_i32 m0, s73, 0xc000
	ds_read_b128 v[202:205], v178
	ds_read_b128 v[206:209], v178 offset:1024
	ds_read_b128 v[210:213], v178 offset:2048
	ds_read_b128 v[214:217], v178 offset:3072
	ds_read_b128 v[218:221], v178 offset:4096
	ds_read_b128 v[222:225], v178 offset:5120
	ds_read_b128 v[226:229], v178 offset:6144
	ds_read_b128 v[230:233], v178 offset:7168
	global_load_lds_dwordx4 v160, s[8:9]
	s_add_i32 m0, s73, 0xe000
	s_nop 0
	global_load_lds_dwordx4 v162, s[8:9]
	s_waitcnt vmcnt(8)
	s_waitcnt lgkmcnt(0)
	.p2align	6
	s_setprio 1
	s_barrier
	v_mfma_f32_16x16x32_bf16 v[126:129], v[130:133], v[202:205], v[126:129]
	v_mfma_f32_16x16x32_bf16 v[122:125], v[170:173], v[202:205], v[122:125]
	v_mfma_f32_16x16x32_bf16 v[110:113], v[130:133], v[210:213], v[110:113]
	v_mfma_f32_16x16x32_bf16 v[106:109], v[170:173], v[210:213], v[106:109]
	v_mfma_f32_16x16x32_bf16 v[94:97], v[130:133], v[218:221], v[94:97]
	v_mfma_f32_16x16x32_bf16 v[90:93], v[170:173], v[218:221], v[90:93]
	v_mfma_f32_16x16x32_bf16 v[78:81], v[130:133], v[226:229], v[78:81]
	v_mfma_f32_16x16x32_bf16 v[74:77], v[170:173], v[226:229], v[74:77]
	v_mfma_f32_16x16x32_bf16 v[126:129], v[134:137], v[206:209], v[126:129]
	v_mfma_f32_16x16x32_bf16 v[122:125], v[180:183], v[206:209], v[122:125]
	v_mfma_f32_16x16x32_bf16 v[110:113], v[134:137], v[214:217], v[110:113]
	v_mfma_f32_16x16x32_bf16 v[106:109], v[180:183], v[214:217], v[106:109]
	v_mfma_f32_16x16x32_bf16 v[94:97], v[134:137], v[222:225], v[94:97]
	v_mfma_f32_16x16x32_bf16 v[90:93], v[180:183], v[222:225], v[90:93]
	v_mfma_f32_16x16x32_bf16 v[78:81], v[134:137], v[230:233], v[78:81]
	v_mfma_f32_16x16x32_bf16 v[74:77], v[180:183], v[230:233], v[74:77]
	v_mfma_f32_16x16x32_bf16 v[118:121], v[184:187], v[202:205], v[118:121]
	v_mfma_f32_16x16x32_bf16 v[114:117], v[192:195], v[202:205], v[114:117]
	v_mfma_f32_16x16x32_bf16 v[102:105], v[184:187], v[210:213], v[102:105]
	v_mfma_f32_16x16x32_bf16 v[98:101], v[192:195], v[210:213], v[98:101]
	v_mfma_f32_16x16x32_bf16 v[86:89], v[184:187], v[218:221], v[86:89]
	v_mfma_f32_16x16x32_bf16 v[82:85], v[192:195], v[218:221], v[82:85]
	v_mfma_f32_16x16x32_bf16 v[70:73], v[184:187], v[226:229], v[70:73]
	v_mfma_f32_16x16x32_bf16 v[66:69], v[192:195], v[226:229], v[66:69]
	v_mfma_f32_16x16x32_bf16 v[118:121], v[188:191], v[206:209], v[118:121]
	v_mfma_f32_16x16x32_bf16 v[114:117], v[198:201], v[206:209], v[114:117]
	v_mfma_f32_16x16x32_bf16 v[102:105], v[188:191], v[214:217], v[102:105]
	v_mfma_f32_16x16x32_bf16 v[98:101], v[198:201], v[214:217], v[98:101]
	v_mfma_f32_16x16x32_bf16 v[86:89], v[188:191], v[222:225], v[86:89]
	v_mfma_f32_16x16x32_bf16 v[82:85], v[198:201], v[222:225], v[82:85]
	v_mfma_f32_16x16x32_bf16 v[70:73], v[188:191], v[230:233], v[70:73]
	v_mfma_f32_16x16x32_bf16 v[66:69], v[198:201], v[230:233], v[66:69]
	s_barrier
	s_setprio 0
	s_add_i32 s30, s69, s35
	s_mov_b32 m0, s30
	ds_read_b128 v[202:205], v178 offset:16384
	ds_read_b128 v[206:209], v178 offset:17408
	ds_read_b128 v[210:213], v178 offset:18432
	ds_read_b128 v[214:217], v178 offset:19456
	ds_read_b128 v[218:221], v178 offset:20480
	ds_read_b128 v[222:225], v178 offset:21504
	ds_read_b128 v[226:229], v178 offset:22528
	ds_read_b128 v[230:233], v178 offset:23552
	global_load_lds_dwordx4 v140, s[14:15]
	s_add_i32 m0, s30, 0x2000
	s_add_u32 s30, s14, 0x100000
	s_addc_u32 s31, s15, 0
	s_add_i32 s38, s70, s35
	global_load_lds_dwordx4 v144, s[14:15]
	s_mov_b32 m0, s38
	global_load_lds_dwordx4 v140, s[30:31]
	s_add_i32 m0, s38, 0x2000
	s_nop 0
	global_load_lds_dwordx4 v144, s[30:31]
	s_mov_b32 m0, s73
	s_nop 0
	global_load_lds_dwordx4 v138, s[18:19]
	s_mov_b32 m0, s66
	s_nop 0
	global_load_lds_dwordx4 v142, s[18:19]
	s_waitcnt vmcnt(8)
	s_waitcnt lgkmcnt(0)
	.p2align	6
	s_setprio 1
	s_barrier
	v_mfma_f32_16x16x32_bf16 v[62:65], v[130:133], v[202:205], v[62:65]
	v_mfma_f32_16x16x32_bf16 v[58:61], v[170:173], v[202:205], v[58:61]
	v_mfma_f32_16x16x32_bf16 v[46:49], v[130:133], v[210:213], v[46:49]
	v_mfma_f32_16x16x32_bf16 v[42:45], v[170:173], v[210:213], v[42:45]
	v_mfma_f32_16x16x32_bf16 v[30:33], v[130:133], v[218:221], v[30:33]
	v_mfma_f32_16x16x32_bf16 v[26:29], v[170:173], v[218:221], v[26:29]
	v_mfma_f32_16x16x32_bf16 v[14:17], v[130:133], v[226:229], v[14:17]
	v_mfma_f32_16x16x32_bf16 v[10:13], v[170:173], v[226:229], v[10:13]
	v_mfma_f32_16x16x32_bf16 v[62:65], v[134:137], v[206:209], v[62:65]
	v_mfma_f32_16x16x32_bf16 v[58:61], v[180:183], v[206:209], v[58:61]
	v_mfma_f32_16x16x32_bf16 v[46:49], v[134:137], v[214:217], v[46:49]
	v_mfma_f32_16x16x32_bf16 v[42:45], v[180:183], v[214:217], v[42:45]
	v_mfma_f32_16x16x32_bf16 v[30:33], v[134:137], v[222:225], v[30:33]
	v_mfma_f32_16x16x32_bf16 v[26:29], v[180:183], v[222:225], v[26:29]
	v_mfma_f32_16x16x32_bf16 v[14:17], v[134:137], v[230:233], v[14:17]
	v_mfma_f32_16x16x32_bf16 v[10:13], v[180:183], v[230:233], v[10:13]
	v_mfma_f32_16x16x32_bf16 v[54:57], v[184:187], v[202:205], v[54:57]
	v_mfma_f32_16x16x32_bf16 v[50:53], v[192:195], v[202:205], v[50:53]
	v_mfma_f32_16x16x32_bf16 v[38:41], v[184:187], v[210:213], v[38:41]
	v_mfma_f32_16x16x32_bf16 v[34:37], v[192:195], v[210:213], v[34:37]
	v_mfma_f32_16x16x32_bf16 v[22:25], v[184:187], v[218:221], v[22:25]
	v_mfma_f32_16x16x32_bf16 v[18:21], v[192:195], v[218:221], v[18:21]
	v_mfma_f32_16x16x32_bf16 v[6:9], v[184:187], v[226:229], v[6:9]
	v_mfma_f32_16x16x32_bf16 v[2:5], v[192:195], v[226:229], v[2:5]
	v_mfma_f32_16x16x32_bf16 v[54:57], v[188:191], v[206:209], v[54:57]
	v_mfma_f32_16x16x32_bf16 v[50:53], v[198:201], v[206:209], v[50:53]
	v_mfma_f32_16x16x32_bf16 v[38:41], v[188:191], v[214:217], v[38:41]
	v_mfma_f32_16x16x32_bf16 v[34:37], v[198:201], v[214:217], v[34:37]
	v_mfma_f32_16x16x32_bf16 v[22:25], v[188:191], v[222:225], v[22:25]
	v_mfma_f32_16x16x32_bf16 v[18:21], v[198:201], v[222:225], v[18:21]
	v_mfma_f32_16x16x32_bf16 v[6:9], v[188:191], v[230:233], v[6:9]
	v_mfma_f32_16x16x32_bf16 v[2:5], v[198:201], v[230:233], v[2:5]
	s_barrier
	s_setprio 0
	s_add_i32 s30, 0, 0x18000
	v_add_u32_e32 v146, s30, v155
	s_add_i32 s31, 0, 0x1c000
	ds_read_b128 v[130:133], v146
	ds_read_b128 v[134:137], v146 offset:1024
	ds_read_b128 v[170:173], v146 offset:2048
	ds_read_b128 v[180:183], v146 offset:3072
	v_add_u32_e32 v146, s31, v155
	ds_read_b128 v[184:187], v146
	ds_read_b128 v[188:191], v146 offset:1024
	ds_read_b128 v[192:195], v146 offset:2048
	ds_read_b128 v[198:201], v146 offset:3072
	s_add_u32 s18, s18, 0x100000
	s_addc_u32 s19, s19, 0
	s_mov_b32 m0, s67
	ds_read_b128 v[202:205], v178 offset:32768
	ds_read_b128 v[206:209], v178 offset:33792
	ds_read_b128 v[210:213], v178 offset:34816
	ds_read_b128 v[214:217], v178 offset:35840
	ds_read_b128 v[218:221], v178 offset:36864
	ds_read_b128 v[222:225], v178 offset:37888
	ds_read_b128 v[226:229], v178 offset:38912
	ds_read_b128 v[230:233], v178 offset:39936
	global_load_lds_dwordx4 v138, s[18:19]
	s_mov_b32 m0, s88
	s_nop 0
	global_load_lds_dwordx4 v142, s[18:19]
	s_waitcnt vmcnt(8)
	s_waitcnt lgkmcnt(0)
	.p2align	6
	s_setprio 1
	s_barrier
	v_mfma_f32_16x16x32_bf16 v[126:129], v[130:133], v[202:205], v[126:129]
	v_mfma_f32_16x16x32_bf16 v[122:125], v[170:173], v[202:205], v[122:125]
	v_mfma_f32_16x16x32_bf16 v[110:113], v[130:133], v[210:213], v[110:113]
	v_mfma_f32_16x16x32_bf16 v[106:109], v[170:173], v[210:213], v[106:109]
	v_mfma_f32_16x16x32_bf16 v[94:97], v[130:133], v[218:221], v[94:97]
	v_mfma_f32_16x16x32_bf16 v[90:93], v[170:173], v[218:221], v[90:93]
	v_mfma_f32_16x16x32_bf16 v[78:81], v[130:133], v[226:229], v[78:81]
	v_mfma_f32_16x16x32_bf16 v[74:77], v[170:173], v[226:229], v[74:77]
	v_mfma_f32_16x16x32_bf16 v[126:129], v[134:137], v[206:209], v[126:129]
	v_mfma_f32_16x16x32_bf16 v[122:125], v[180:183], v[206:209], v[122:125]
	v_mfma_f32_16x16x32_bf16 v[110:113], v[134:137], v[214:217], v[110:113]
	v_mfma_f32_16x16x32_bf16 v[106:109], v[180:183], v[214:217], v[106:109]
	v_mfma_f32_16x16x32_bf16 v[94:97], v[134:137], v[222:225], v[94:97]
	v_mfma_f32_16x16x32_bf16 v[90:93], v[180:183], v[222:225], v[90:93]
	v_mfma_f32_16x16x32_bf16 v[78:81], v[134:137], v[230:233], v[78:81]
	v_mfma_f32_16x16x32_bf16 v[74:77], v[180:183], v[230:233], v[74:77]
	v_mfma_f32_16x16x32_bf16 v[118:121], v[184:187], v[202:205], v[118:121]
	v_mfma_f32_16x16x32_bf16 v[114:117], v[192:195], v[202:205], v[114:117]
	v_mfma_f32_16x16x32_bf16 v[102:105], v[184:187], v[210:213], v[102:105]
	v_mfma_f32_16x16x32_bf16 v[98:101], v[192:195], v[210:213], v[98:101]
	v_mfma_f32_16x16x32_bf16 v[86:89], v[184:187], v[218:221], v[86:89]
	v_mfma_f32_16x16x32_bf16 v[82:85], v[192:195], v[218:221], v[82:85]
	v_mfma_f32_16x16x32_bf16 v[70:73], v[184:187], v[226:229], v[70:73]
	v_mfma_f32_16x16x32_bf16 v[66:69], v[192:195], v[226:229], v[66:69]
	v_mfma_f32_16x16x32_bf16 v[118:121], v[188:191], v[206:209], v[118:121]
	v_mfma_f32_16x16x32_bf16 v[114:117], v[198:201], v[206:209], v[114:117]
	v_mfma_f32_16x16x32_bf16 v[102:105], v[188:191], v[214:217], v[102:105]
	v_mfma_f32_16x16x32_bf16 v[98:101], v[198:201], v[214:217], v[98:101]
	v_mfma_f32_16x16x32_bf16 v[86:89], v[188:191], v[222:225], v[86:89]
	v_mfma_f32_16x16x32_bf16 v[82:85], v[198:201], v[222:225], v[82:85]
	v_mfma_f32_16x16x32_bf16 v[70:73], v[188:191], v[230:233], v[70:73]
	v_mfma_f32_16x16x32_bf16 v[66:69], v[198:201], v[230:233], v[66:69]
	s_barrier
	s_setprio 0
	s_add_u32 s14, s14, 0x80
	s_addc_u32 s15, s15, 0
	s_add_i32 m0, s35, 0x18000
	ds_read_b128 v[202:205], v178 offset:49152
	ds_read_b128 v[206:209], v178 offset:50176
	ds_read_b128 v[210:213], v178 offset:51200
	ds_read_b128 v[214:217], v178 offset:52224
	ds_read_b128 v[218:221], v178 offset:53248
	ds_read_b128 v[222:225], v178 offset:54272
	ds_read_b128 v[226:229], v178 offset:55296
	ds_read_b128 v[230:233], v178 offset:56320
	global_load_lds_dwordx4 v140, s[14:15]
	s_add_i32 m0, s35, 0x1a000
	s_add_u32 s18, s18, 0xfff00080
	global_load_lds_dwordx4 v144, s[14:15]
	s_addc_u32 s19, s19, -1
	s_add_u32 s14, s14, 0x100000
	s_addc_u32 s15, s15, 0
	s_add_i32 m0, s35, 0x1c000
	s_nop 0
	global_load_lds_dwordx4 v140, s[14:15]
	s_add_i32 m0, s35, 0x1e000
	s_nop 0
	global_load_lds_dwordx4 v144, s[14:15]
	s_mov_b32 m0, s89
	s_nop 0
	global_load_lds_dwordx4 v138, s[18:19]
	s_mov_b32 m0, s68
	s_nop 0
	global_load_lds_dwordx4 v142, s[18:19]
	s_waitcnt vmcnt(8)
	s_waitcnt lgkmcnt(0)
	.p2align	6
	s_setprio 1
	s_barrier
	v_mfma_f32_16x16x32_bf16 v[62:65], v[130:133], v[202:205], v[62:65]
	v_mfma_f32_16x16x32_bf16 v[58:61], v[170:173], v[202:205], v[58:61]
	v_mfma_f32_16x16x32_bf16 v[46:49], v[130:133], v[210:213], v[46:49]
	v_mfma_f32_16x16x32_bf16 v[42:45], v[170:173], v[210:213], v[42:45]
	v_mfma_f32_16x16x32_bf16 v[30:33], v[130:133], v[218:221], v[30:33]
	v_mfma_f32_16x16x32_bf16 v[26:29], v[170:173], v[218:221], v[26:29]
	v_mfma_f32_16x16x32_bf16 v[14:17], v[130:133], v[226:229], v[14:17]
	v_mfma_f32_16x16x32_bf16 v[10:13], v[170:173], v[226:229], v[10:13]
	v_mfma_f32_16x16x32_bf16 v[62:65], v[134:137], v[206:209], v[62:65]
	v_mfma_f32_16x16x32_bf16 v[58:61], v[180:183], v[206:209], v[58:61]
	v_mfma_f32_16x16x32_bf16 v[46:49], v[134:137], v[214:217], v[46:49]
	v_mfma_f32_16x16x32_bf16 v[42:45], v[180:183], v[214:217], v[42:45]
	v_mfma_f32_16x16x32_bf16 v[30:33], v[134:137], v[222:225], v[30:33]
	v_mfma_f32_16x16x32_bf16 v[26:29], v[180:183], v[222:225], v[26:29]
	v_mfma_f32_16x16x32_bf16 v[14:17], v[134:137], v[230:233], v[14:17]
	v_mfma_f32_16x16x32_bf16 v[10:13], v[180:183], v[230:233], v[10:13]
	v_mfma_f32_16x16x32_bf16 v[54:57], v[184:187], v[202:205], v[54:57]
	v_mfma_f32_16x16x32_bf16 v[50:53], v[192:195], v[202:205], v[50:53]
	v_mfma_f32_16x16x32_bf16 v[38:41], v[184:187], v[210:213], v[38:41]
	v_mfma_f32_16x16x32_bf16 v[34:37], v[192:195], v[210:213], v[34:37]
	v_mfma_f32_16x16x32_bf16 v[22:25], v[184:187], v[218:221], v[22:25]
	v_mfma_f32_16x16x32_bf16 v[18:21], v[192:195], v[218:221], v[18:21]
	v_mfma_f32_16x16x32_bf16 v[6:9], v[184:187], v[226:229], v[6:9]
	v_mfma_f32_16x16x32_bf16 v[2:5], v[192:195], v[226:229], v[2:5]
	v_mfma_f32_16x16x32_bf16 v[54:57], v[188:191], v[206:209], v[54:57]
	v_mfma_f32_16x16x32_bf16 v[50:53], v[198:201], v[206:209], v[50:53]
	v_mfma_f32_16x16x32_bf16 v[38:41], v[188:191], v[214:217], v[38:41]
	v_mfma_f32_16x16x32_bf16 v[34:37], v[198:201], v[214:217], v[34:37]
	v_mfma_f32_16x16x32_bf16 v[22:25], v[188:191], v[222:225], v[22:25]
	v_mfma_f32_16x16x32_bf16 v[18:21], v[198:201], v[222:225], v[18:21]
	v_mfma_f32_16x16x32_bf16 v[6:9], v[188:191], v[230:233], v[6:9]
	v_mfma_f32_16x16x32_bf16 v[2:5], v[198:201], v[230:233], v[2:5]
	s_barrier
	s_setprio 0
	s_add_i32 s29, s29, 2
	s_add_u32 s8, s8, 0x100
	s_addc_u32 s9, s9, 0
	s_add_u32 s21, s21, 0x100
	s_addc_u32 s28, s28, 0
	s_cmp_gt_u32 s29, 61
	s_cbranch_scc0 .LBB0_126
	v_readlane_b32 s8, v249, 56
	v_readlane_b32 s9, v249, 57
	s_and_b64 vcc, exec, s[8:9]
	s_cbranch_vccz .LBB0_129
	s_barrier

.LBB0_678:
	ds_read_b128 v[148:151], v159
	ds_read_b128 v[152:155], v159 offset:1024
	ds_read_b128 v[164:167], v159 offset:2048
	ds_read_b128 v[168:171], v159 offset:3072
	ds_read_b128 v[172:175], v160
	ds_read_b128 v[176:179], v160 offset:1024
	ds_read_b128 v[180:183], v160 offset:2048
	ds_read_b128 v[184:187], v160 offset:3072
	s_add_u32 s60, s58, 0xfff00080
	s_addc_u32 s61, s59, -1
	s_cmp_eq_u32 s78, 60
	s_cselect_b32 s63, s7, s61
	s_cselect_b32 s62, s47, s60
	s_cselect_b32 s61, s45, s77
	s_cselect_b32 s60, s57, s76
	s_add_i32 m0, s64, 0xc000
	ds_read_b128 v[188:191], v161
	ds_read_b128 v[192:195], v161 offset:1024
	ds_read_b128 v[198:201], v161 offset:2048
	ds_read_b128 v[202:205], v161 offset:3072
	ds_read_b128 v[206:209], v161 offset:4096
	ds_read_b128 v[210:213], v161 offset:5120
	ds_read_b128 v[214:217], v161 offset:6144
	ds_read_b128 v[218:221], v161 offset:7168
	global_load_lds_dwordx4 v140, s[58:59]
	s_add_i32 m0, s64, 0xe000
	s_nop 0
	global_load_lds_dwordx4 v142, s[58:59]
	s_waitcnt vmcnt(8)
	s_waitcnt lgkmcnt(0)
	.p2align	6
	s_setprio 1
	s_barrier
	v_mfma_f32_16x16x32_bf16 v[126:129], v[148:151], v[188:191], v[126:129]
	v_mfma_f32_16x16x32_bf16 v[122:125], v[164:167], v[188:191], v[122:125]
	v_mfma_f32_16x16x32_bf16 v[110:113], v[148:151], v[198:201], v[110:113]
	v_mfma_f32_16x16x32_bf16 v[106:109], v[164:167], v[198:201], v[106:109]
	v_mfma_f32_16x16x32_bf16 v[94:97], v[148:151], v[206:209], v[94:97]
	v_mfma_f32_16x16x32_bf16 v[90:93], v[164:167], v[206:209], v[90:93]
	v_mfma_f32_16x16x32_bf16 v[78:81], v[148:151], v[214:217], v[78:81]
	v_mfma_f32_16x16x32_bf16 v[74:77], v[164:167], v[214:217], v[74:77]
	v_mfma_f32_16x16x32_bf16 v[126:129], v[152:155], v[192:195], v[126:129]
	v_mfma_f32_16x16x32_bf16 v[122:125], v[168:171], v[192:195], v[122:125]
	v_mfma_f32_16x16x32_bf16 v[110:113], v[152:155], v[202:205], v[110:113]
	v_mfma_f32_16x16x32_bf16 v[106:109], v[168:171], v[202:205], v[106:109]
	v_mfma_f32_16x16x32_bf16 v[94:97], v[152:155], v[210:213], v[94:97]
	v_mfma_f32_16x16x32_bf16 v[90:93], v[168:171], v[210:213], v[90:93]
	v_mfma_f32_16x16x32_bf16 v[78:81], v[152:155], v[218:221], v[78:81]
	v_mfma_f32_16x16x32_bf16 v[74:77], v[168:171], v[218:221], v[74:77]
	v_mfma_f32_16x16x32_bf16 v[118:121], v[172:175], v[188:191], v[118:121]
	v_mfma_f32_16x16x32_bf16 v[114:117], v[180:183], v[188:191], v[114:117]
	v_mfma_f32_16x16x32_bf16 v[102:105], v[172:175], v[198:201], v[102:105]
	v_mfma_f32_16x16x32_bf16 v[98:101], v[180:183], v[198:201], v[98:101]
	v_mfma_f32_16x16x32_bf16 v[86:89], v[172:175], v[206:209], v[86:89]
	v_mfma_f32_16x16x32_bf16 v[82:85], v[180:183], v[206:209], v[82:85]
	v_mfma_f32_16x16x32_bf16 v[70:73], v[172:175], v[214:217], v[70:73]
	v_mfma_f32_16x16x32_bf16 v[66:69], v[180:183], v[214:217], v[66:69]
	v_mfma_f32_16x16x32_bf16 v[118:121], v[176:179], v[192:195], v[118:121]
	v_mfma_f32_16x16x32_bf16 v[114:117], v[184:187], v[192:195], v[114:117]
	v_mfma_f32_16x16x32_bf16 v[102:105], v[176:179], v[202:205], v[102:105]
	v_mfma_f32_16x16x32_bf16 v[98:101], v[184:187], v[202:205], v[98:101]
	v_mfma_f32_16x16x32_bf16 v[86:89], v[176:179], v[210:213], v[86:89]
	v_mfma_f32_16x16x32_bf16 v[82:85], v[184:187], v[210:213], v[82:85]
	v_mfma_f32_16x16x32_bf16 v[70:73], v[176:179], v[218:221], v[70:73]
	v_mfma_f32_16x16x32_bf16 v[66:69], v[184:187], v[218:221], v[66:69]
	s_barrier
	s_setprio 0
	s_add_i32 s79, s74, s33
	s_mov_b32 m0, s79
	ds_read_b128 v[188:191], v161 offset:16384
	ds_read_b128 v[192:195], v161 offset:17408
	ds_read_b128 v[198:201], v161 offset:18432
	ds_read_b128 v[202:205], v161 offset:19456
	ds_read_b128 v[206:209], v161 offset:20480
	ds_read_b128 v[210:213], v161 offset:21504
	ds_read_b128 v[214:217], v161 offset:22528
	ds_read_b128 v[218:221], v161 offset:23552
	global_load_lds_dwordx4 v132, s[60:61]
	s_add_i32 m0, s79, 0x2000
	s_add_u32 s80, s60, 0x100000
	s_addc_u32 s81, s61, 0
	s_add_i32 s79, s75, s33
	global_load_lds_dwordx4 v136, s[60:61]
	s_mov_b32 m0, s79
	global_load_lds_dwordx4 v132, s[80:81]
	s_add_i32 m0, s79, 0x2000
	s_nop 0
	global_load_lds_dwordx4 v136, s[80:81]
	s_mov_b32 m0, s64
	s_nop 0
	global_load_lds_dwordx4 v130, s[62:63]
	s_mov_b32 m0, s65
	s_nop 0
	global_load_lds_dwordx4 v134, s[62:63]
	s_waitcnt vmcnt(8)
	s_waitcnt lgkmcnt(0)
	.p2align	6
	s_setprio 1
	s_barrier
	v_mfma_f32_16x16x32_bf16 v[62:65], v[148:151], v[188:191], v[62:65]
	v_mfma_f32_16x16x32_bf16 v[58:61], v[164:167], v[188:191], v[58:61]
	v_mfma_f32_16x16x32_bf16 v[46:49], v[148:151], v[198:201], v[46:49]
	v_mfma_f32_16x16x32_bf16 v[42:45], v[164:167], v[198:201], v[42:45]
	v_mfma_f32_16x16x32_bf16 v[30:33], v[148:151], v[206:209], v[30:33]
	v_mfma_f32_16x16x32_bf16 v[26:29], v[164:167], v[206:209], v[26:29]
	v_mfma_f32_16x16x32_bf16 v[14:17], v[148:151], v[214:217], v[14:17]
	v_mfma_f32_16x16x32_bf16 v[10:13], v[164:167], v[214:217], v[10:13]
	v_mfma_f32_16x16x32_bf16 v[62:65], v[152:155], v[192:195], v[62:65]
	v_mfma_f32_16x16x32_bf16 v[58:61], v[168:171], v[192:195], v[58:61]
	v_mfma_f32_16x16x32_bf16 v[46:49], v[152:155], v[202:205], v[46:49]
	v_mfma_f32_16x16x32_bf16 v[42:45], v[168:171], v[202:205], v[42:45]
	v_mfma_f32_16x16x32_bf16 v[30:33], v[152:155], v[210:213], v[30:33]
	v_mfma_f32_16x16x32_bf16 v[26:29], v[168:171], v[210:213], v[26:29]
	v_mfma_f32_16x16x32_bf16 v[14:17], v[152:155], v[218:221], v[14:17]
	v_mfma_f32_16x16x32_bf16 v[10:13], v[168:171], v[218:221], v[10:13]
	v_mfma_f32_16x16x32_bf16 v[54:57], v[172:175], v[188:191], v[54:57]
	v_mfma_f32_16x16x32_bf16 v[50:53], v[180:183], v[188:191], v[50:53]
	v_mfma_f32_16x16x32_bf16 v[38:41], v[172:175], v[198:201], v[38:41]
	v_mfma_f32_16x16x32_bf16 v[34:37], v[180:183], v[198:201], v[34:37]
	v_mfma_f32_16x16x32_bf16 v[22:25], v[172:175], v[206:209], v[22:25]
	v_mfma_f32_16x16x32_bf16 v[18:21], v[180:183], v[206:209], v[18:21]
	v_mfma_f32_16x16x32_bf16 v[6:9], v[172:175], v[214:217], v[6:9]
	v_mfma_f32_16x16x32_bf16 v[2:5], v[180:183], v[214:217], v[2:5]
	v_mfma_f32_16x16x32_bf16 v[54:57], v[176:179], v[192:195], v[54:57]
	v_mfma_f32_16x16x32_bf16 v[50:53], v[184:187], v[192:195], v[50:53]
	v_mfma_f32_16x16x32_bf16 v[38:41], v[176:179], v[202:205], v[38:41]
	v_mfma_f32_16x16x32_bf16 v[34:37], v[184:187], v[202:205], v[34:37]
	v_mfma_f32_16x16x32_bf16 v[22:25], v[176:179], v[210:213], v[22:25]
	v_mfma_f32_16x16x32_bf16 v[18:21], v[184:187], v[210:213], v[18:21]
	v_mfma_f32_16x16x32_bf16 v[6:9], v[176:179], v[218:221], v[6:9]
	v_mfma_f32_16x16x32_bf16 v[2:5], v[184:187], v[218:221], v[2:5]
	s_barrier
	s_setprio 0
	s_add_i32 s79, 0, 0x18000
	v_add_u32_e32 v138, s79, v157
	s_add_i32 s80, 0, 0x1c000
	ds_read_b128 v[148:151], v138
	ds_read_b128 v[152:155], v138 offset:1024
	ds_read_b128 v[164:167], v138 offset:2048
	ds_read_b128 v[168:171], v138 offset:3072
	v_add_u32_e32 v138, s80, v157
	ds_read_b128 v[172:175], v138
	ds_read_b128 v[176:179], v138 offset:1024
	ds_read_b128 v[180:183], v138 offset:2048
	ds_read_b128 v[184:187], v138 offset:3072
	s_add_u32 s62, s62, 0x100000
	s_addc_u32 s63, s63, 0
	s_mov_b32 m0, s66
	ds_read_b128 v[188:191], v161 offset:32768
	ds_read_b128 v[192:195], v161 offset:33792
	ds_read_b128 v[198:201], v161 offset:34816
	ds_read_b128 v[202:205], v161 offset:35840
	ds_read_b128 v[206:209], v161 offset:36864
	ds_read_b128 v[210:213], v161 offset:37888
	ds_read_b128 v[214:217], v161 offset:38912
	ds_read_b128 v[218:221], v161 offset:39936
	global_load_lds_dwordx4 v130, s[62:63]
	s_mov_b32 m0, s67
	s_nop 0
	global_load_lds_dwordx4 v134, s[62:63]
	s_waitcnt vmcnt(8)
	s_waitcnt lgkmcnt(0)
	.p2align	6
	s_setprio 1
	s_barrier
	v_mfma_f32_16x16x32_bf16 v[126:129], v[148:151], v[188:191], v[126:129]
	v_mfma_f32_16x16x32_bf16 v[122:125], v[164:167], v[188:191], v[122:125]
	v_mfma_f32_16x16x32_bf16 v[110:113], v[148:151], v[198:201], v[110:113]
	v_mfma_f32_16x16x32_bf16 v[106:109], v[164:167], v[198:201], v[106:109]
	v_mfma_f32_16x16x32_bf16 v[94:97], v[148:151], v[206:209], v[94:97]
	v_mfma_f32_16x16x32_bf16 v[90:93], v[164:167], v[206:209], v[90:93]
	v_mfma_f32_16x16x32_bf16 v[78:81], v[148:151], v[214:217], v[78:81]
	v_mfma_f32_16x16x32_bf16 v[74:77], v[164:167], v[214:217], v[74:77]
	v_mfma_f32_16x16x32_bf16 v[126:129], v[152:155], v[192:195], v[126:129]
	v_mfma_f32_16x16x32_bf16 v[122:125], v[168:171], v[192:195], v[122:125]
	v_mfma_f32_16x16x32_bf16 v[110:113], v[152:155], v[202:205], v[110:113]
	v_mfma_f32_16x16x32_bf16 v[106:109], v[168:171], v[202:205], v[106:109]
	v_mfma_f32_16x16x32_bf16 v[94:97], v[152:155], v[210:213], v[94:97]
	v_mfma_f32_16x16x32_bf16 v[90:93], v[168:171], v[210:213], v[90:93]
	v_mfma_f32_16x16x32_bf16 v[78:81], v[152:155], v[218:221], v[78:81]
	v_mfma_f32_16x16x32_bf16 v[74:77], v[168:171], v[218:221], v[74:77]
	v_mfma_f32_16x16x32_bf16 v[118:121], v[172:175], v[188:191], v[118:121]
	v_mfma_f32_16x16x32_bf16 v[114:117], v[180:183], v[188:191], v[114:117]
	v_mfma_f32_16x16x32_bf16 v[102:105], v[172:175], v[198:201], v[102:105]
	v_mfma_f32_16x16x32_bf16 v[98:101], v[180:183], v[198:201], v[98:101]
	v_mfma_f32_16x16x32_bf16 v[86:89], v[172:175], v[206:209], v[86:89]
	v_mfma_f32_16x16x32_bf16 v[82:85], v[180:183], v[206:209], v[82:85]
	v_mfma_f32_16x16x32_bf16 v[70:73], v[172:175], v[214:217], v[70:73]
	v_mfma_f32_16x16x32_bf16 v[66:69], v[180:183], v[214:217], v[66:69]
	v_mfma_f32_16x16x32_bf16 v[118:121], v[176:179], v[192:195], v[118:121]
	v_mfma_f32_16x16x32_bf16 v[114:117], v[184:187], v[192:195], v[114:117]
	v_mfma_f32_16x16x32_bf16 v[102:105], v[176:179], v[202:205], v[102:105]
	v_mfma_f32_16x16x32_bf16 v[98:101], v[184:187], v[202:205], v[98:101]
	v_mfma_f32_16x16x32_bf16 v[86:89], v[176:179], v[210:213], v[86:89]
	v_mfma_f32_16x16x32_bf16 v[82:85], v[184:187], v[210:213], v[82:85]
	v_mfma_f32_16x16x32_bf16 v[70:73], v[176:179], v[218:221], v[70:73]
	v_mfma_f32_16x16x32_bf16 v[66:69], v[184:187], v[218:221], v[66:69]
	s_barrier
	s_setprio 0
	s_add_u32 s60, s60, 0x80
	s_addc_u32 s61, s61, 0
	s_add_i32 m0, s33, 0x18000
	ds_read_b128 v[188:191], v161 offset:49152
	ds_read_b128 v[192:195], v161 offset:50176
	ds_read_b128 v[198:201], v161 offset:51200
	ds_read_b128 v[202:205], v161 offset:52224
	ds_read_b128 v[206:209], v161 offset:53248
	ds_read_b128 v[210:213], v161 offset:54272
	ds_read_b128 v[214:217], v161 offset:55296
	ds_read_b128 v[218:221], v161 offset:56320
	global_load_lds_dwordx4 v132, s[60:61]
	s_add_i32 m0, s33, 0x1a000
	s_add_u32 s62, s62, 0xfff00080
	global_load_lds_dwordx4 v136, s[60:61]
	s_addc_u32 s63, s63, -1
	s_add_u32 s60, s60, 0x100000
	s_addc_u32 s61, s61, 0
	s_add_i32 m0, s33, 0x1c000
	s_nop 0
	global_load_lds_dwordx4 v132, s[60:61]
	s_add_i32 m0, s33, 0x1e000
	s_nop 0
	global_load_lds_dwordx4 v136, s[60:61]
	s_mov_b32 m0, s69
	s_nop 0
	global_load_lds_dwordx4 v130, s[62:63]
	s_mov_b32 m0, s70
	s_nop 0
	global_load_lds_dwordx4 v134, s[62:63]
	s_waitcnt vmcnt(8)
	s_waitcnt lgkmcnt(0)
	.p2align	6
	s_setprio 1
	s_barrier
	v_mfma_f32_16x16x32_bf16 v[62:65], v[148:151], v[188:191], v[62:65]
	v_mfma_f32_16x16x32_bf16 v[58:61], v[164:167], v[188:191], v[58:61]
	v_mfma_f32_16x16x32_bf16 v[46:49], v[148:151], v[198:201], v[46:49]
	v_mfma_f32_16x16x32_bf16 v[42:45], v[164:167], v[198:201], v[42:45]
	v_mfma_f32_16x16x32_bf16 v[30:33], v[148:151], v[206:209], v[30:33]
	v_mfma_f32_16x16x32_bf16 v[26:29], v[164:167], v[206:209], v[26:29]
	v_mfma_f32_16x16x32_bf16 v[14:17], v[148:151], v[214:217], v[14:17]
	v_mfma_f32_16x16x32_bf16 v[10:13], v[164:167], v[214:217], v[10:13]
	v_mfma_f32_16x16x32_bf16 v[62:65], v[152:155], v[192:195], v[62:65]
	v_mfma_f32_16x16x32_bf16 v[58:61], v[168:171], v[192:195], v[58:61]
	v_mfma_f32_16x16x32_bf16 v[46:49], v[152:155], v[202:205], v[46:49]
	v_mfma_f32_16x16x32_bf16 v[42:45], v[168:171], v[202:205], v[42:45]
	v_mfma_f32_16x16x32_bf16 v[30:33], v[152:155], v[210:213], v[30:33]
	v_mfma_f32_16x16x32_bf16 v[26:29], v[168:171], v[210:213], v[26:29]
	v_mfma_f32_16x16x32_bf16 v[14:17], v[152:155], v[218:221], v[14:17]
	v_mfma_f32_16x16x32_bf16 v[10:13], v[168:171], v[218:221], v[10:13]
	v_mfma_f32_16x16x32_bf16 v[54:57], v[172:175], v[188:191], v[54:57]
	v_mfma_f32_16x16x32_bf16 v[50:53], v[180:183], v[188:191], v[50:53]
	v_mfma_f32_16x16x32_bf16 v[38:41], v[172:175], v[198:201], v[38:41]
	v_mfma_f32_16x16x32_bf16 v[34:37], v[180:183], v[198:201], v[34:37]
	v_mfma_f32_16x16x32_bf16 v[22:25], v[172:175], v[206:209], v[22:25]
	v_mfma_f32_16x16x32_bf16 v[18:21], v[180:183], v[206:209], v[18:21]
	v_mfma_f32_16x16x32_bf16 v[6:9], v[172:175], v[214:217], v[6:9]
	v_mfma_f32_16x16x32_bf16 v[2:5], v[180:183], v[214:217], v[2:5]
	v_mfma_f32_16x16x32_bf16 v[54:57], v[176:179], v[192:195], v[54:57]
	v_mfma_f32_16x16x32_bf16 v[50:53], v[184:187], v[192:195], v[50:53]
	v_mfma_f32_16x16x32_bf16 v[38:41], v[176:179], v[202:205], v[38:41]
	v_mfma_f32_16x16x32_bf16 v[34:37], v[184:187], v[202:205], v[34:37]
	v_mfma_f32_16x16x32_bf16 v[22:25], v[176:179], v[210:213], v[22:25]
	v_mfma_f32_16x16x32_bf16 v[18:21], v[184:187], v[210:213], v[18:21]
	v_mfma_f32_16x16x32_bf16 v[6:9], v[176:179], v[218:221], v[6:9]
	v_mfma_f32_16x16x32_bf16 v[2:5], v[184:187], v[218:221], v[2:5]
	s_barrier
	s_setprio 0
	s_add_i32 s78, s78, 2
	s_add_u32 s58, s58, 0x100
	s_addc_u32 s59, s59, 0
	s_add_u32 s76, s76, 0x100
	s_addc_u32 s77, s77, 0
	s_cmp_gt_u32 s78, 61
	s_cbranch_scc0 .LBB0_678
	s_and_b64 vcc, exec, s[18:19]
	s_cbranch_vccz .LBB0_681
	s_barrier

.LBB0_807:
	ds_read_b128 v[154:157], v150
	ds_read_b128 v[158:161], v150 offset:1024
	ds_read_b128 v[162:165], v150 offset:2048
	ds_read_b128 v[166:169], v150 offset:3072
	ds_read_b128 v[170:173], v151
	ds_read_b128 v[174:177], v151 offset:1024
	ds_read_b128 v[178:181], v151 offset:2048
	ds_read_b128 v[182:185], v151 offset:3072
	s_add_u32 s44, s42, 0xfff00080
	s_addc_u32 s45, s43, -1
	s_cmp_eq_u32 s68, 60
	s_cselect_b32 s47, s35, s45
	s_cselect_b32 s46, s64, s44
	s_cselect_b32 s45, s31, s67
	s_cselect_b32 s44, s65, s66
	s_add_i32 m0, s41, 0xc000
	ds_read_b128 v[186:189], v152
	ds_read_b128 v[190:193], v152 offset:1024
	ds_read_b128 v[198:201], v152 offset:2048
	ds_read_b128 v[202:205], v152 offset:3072
	ds_read_b128 v[206:209], v152 offset:4096
	ds_read_b128 v[210:213], v152 offset:5120
	ds_read_b128 v[214:217], v152 offset:6144
	ds_read_b128 v[218:221], v152 offset:7168
	global_load_lds_dwordx4 v138, s[42:43]
	s_add_i32 m0, s41, 0xe000
	s_nop 0
	global_load_lds_dwordx4 v140, s[42:43]
	s_waitcnt vmcnt(8)
	s_waitcnt lgkmcnt(0)
	.p2align	6
	s_setprio 1
	s_barrier
	v_mfma_f32_16x16x32_bf16 v[126:129], v[154:157], v[186:189], v[126:129]
	v_mfma_f32_16x16x32_bf16 v[122:125], v[162:165], v[186:189], v[122:125]
	v_mfma_f32_16x16x32_bf16 v[110:113], v[154:157], v[198:201], v[110:113]
	v_mfma_f32_16x16x32_bf16 v[106:109], v[162:165], v[198:201], v[106:109]
	v_mfma_f32_16x16x32_bf16 v[94:97], v[154:157], v[206:209], v[94:97]
	v_mfma_f32_16x16x32_bf16 v[90:93], v[162:165], v[206:209], v[90:93]
	v_mfma_f32_16x16x32_bf16 v[78:81], v[154:157], v[214:217], v[78:81]
	v_mfma_f32_16x16x32_bf16 v[74:77], v[162:165], v[214:217], v[74:77]
	v_mfma_f32_16x16x32_bf16 v[126:129], v[158:161], v[190:193], v[126:129]
	v_mfma_f32_16x16x32_bf16 v[122:125], v[166:169], v[190:193], v[122:125]
	v_mfma_f32_16x16x32_bf16 v[110:113], v[158:161], v[202:205], v[110:113]
	v_mfma_f32_16x16x32_bf16 v[106:109], v[166:169], v[202:205], v[106:109]
	v_mfma_f32_16x16x32_bf16 v[94:97], v[158:161], v[210:213], v[94:97]
	v_mfma_f32_16x16x32_bf16 v[90:93], v[166:169], v[210:213], v[90:93]
	v_mfma_f32_16x16x32_bf16 v[78:81], v[158:161], v[218:221], v[78:81]
	v_mfma_f32_16x16x32_bf16 v[74:77], v[166:169], v[218:221], v[74:77]
	v_mfma_f32_16x16x32_bf16 v[118:121], v[170:173], v[186:189], v[118:121]
	v_mfma_f32_16x16x32_bf16 v[114:117], v[178:181], v[186:189], v[114:117]
	v_mfma_f32_16x16x32_bf16 v[102:105], v[170:173], v[198:201], v[102:105]
	v_mfma_f32_16x16x32_bf16 v[98:101], v[178:181], v[198:201], v[98:101]
	v_mfma_f32_16x16x32_bf16 v[86:89], v[170:173], v[206:209], v[86:89]
	v_mfma_f32_16x16x32_bf16 v[82:85], v[178:181], v[206:209], v[82:85]
	v_mfma_f32_16x16x32_bf16 v[70:73], v[170:173], v[214:217], v[70:73]
	v_mfma_f32_16x16x32_bf16 v[66:69], v[178:181], v[214:217], v[66:69]
	v_mfma_f32_16x16x32_bf16 v[118:121], v[174:177], v[190:193], v[118:121]
	v_mfma_f32_16x16x32_bf16 v[114:117], v[182:185], v[190:193], v[114:117]
	v_mfma_f32_16x16x32_bf16 v[102:105], v[174:177], v[202:205], v[102:105]
	v_mfma_f32_16x16x32_bf16 v[98:101], v[182:185], v[202:205], v[98:101]
	v_mfma_f32_16x16x32_bf16 v[86:89], v[174:177], v[210:213], v[86:89]
	v_mfma_f32_16x16x32_bf16 v[82:85], v[182:185], v[210:213], v[82:85]
	v_mfma_f32_16x16x32_bf16 v[70:73], v[174:177], v[218:221], v[70:73]
	v_mfma_f32_16x16x32_bf16 v[66:69], v[182:185], v[218:221], v[66:69]
	s_barrier
	s_setprio 0
	s_add_i32 s69, s57, s33
	s_mov_b32 m0, s69
	ds_read_b128 v[186:189], v152 offset:16384
	ds_read_b128 v[190:193], v152 offset:17408
	ds_read_b128 v[198:201], v152 offset:18432
	ds_read_b128 v[202:205], v152 offset:19456
	ds_read_b128 v[206:209], v152 offset:20480
	ds_read_b128 v[210:213], v152 offset:21504
	ds_read_b128 v[214:217], v152 offset:22528
	ds_read_b128 v[218:221], v152 offset:23552
	global_load_lds_dwordx4 v132, s[44:45]
	s_add_i32 m0, s69, 0x2000
	s_add_u32 s70, s44, 0x100000
	s_addc_u32 s71, s45, 0
	s_add_i32 s69, s58, s33
	global_load_lds_dwordx4 v136, s[44:45]
	s_mov_b32 m0, s69
	global_load_lds_dwordx4 v132, s[70:71]
	s_add_i32 m0, s69, 0x2000
	s_nop 0
	global_load_lds_dwordx4 v136, s[70:71]
	s_mov_b32 m0, s41
	s_nop 0
	global_load_lds_dwordx4 v130, s[46:47]
	s_mov_b32 m0, s50
	s_nop 0
	global_load_lds_dwordx4 v134, s[46:47]
	s_waitcnt vmcnt(8)
	s_waitcnt lgkmcnt(0)
	.p2align	6
	s_setprio 1
	s_barrier
	v_mfma_f32_16x16x32_bf16 v[62:65], v[154:157], v[186:189], v[62:65]
	v_mfma_f32_16x16x32_bf16 v[58:61], v[162:165], v[186:189], v[58:61]
	v_mfma_f32_16x16x32_bf16 v[46:49], v[154:157], v[198:201], v[46:49]
	v_mfma_f32_16x16x32_bf16 v[42:45], v[162:165], v[198:201], v[42:45]
	v_mfma_f32_16x16x32_bf16 v[30:33], v[154:157], v[206:209], v[30:33]
	v_mfma_f32_16x16x32_bf16 v[26:29], v[162:165], v[206:209], v[26:29]
	v_mfma_f32_16x16x32_bf16 v[14:17], v[154:157], v[214:217], v[14:17]
	v_mfma_f32_16x16x32_bf16 v[10:13], v[162:165], v[214:217], v[10:13]
	v_mfma_f32_16x16x32_bf16 v[62:65], v[158:161], v[190:193], v[62:65]
	v_mfma_f32_16x16x32_bf16 v[58:61], v[166:169], v[190:193], v[58:61]
	v_mfma_f32_16x16x32_bf16 v[46:49], v[158:161], v[202:205], v[46:49]
	v_mfma_f32_16x16x32_bf16 v[42:45], v[166:169], v[202:205], v[42:45]
	v_mfma_f32_16x16x32_bf16 v[30:33], v[158:161], v[210:213], v[30:33]
	v_mfma_f32_16x16x32_bf16 v[26:29], v[166:169], v[210:213], v[26:29]
	v_mfma_f32_16x16x32_bf16 v[14:17], v[158:161], v[218:221], v[14:17]
	v_mfma_f32_16x16x32_bf16 v[10:13], v[166:169], v[218:221], v[10:13]
	v_mfma_f32_16x16x32_bf16 v[54:57], v[170:173], v[186:189], v[54:57]
	v_mfma_f32_16x16x32_bf16 v[50:53], v[178:181], v[186:189], v[50:53]
	v_mfma_f32_16x16x32_bf16 v[38:41], v[170:173], v[198:201], v[38:41]
	v_mfma_f32_16x16x32_bf16 v[34:37], v[178:181], v[198:201], v[34:37]
	v_mfma_f32_16x16x32_bf16 v[22:25], v[170:173], v[206:209], v[22:25]
	v_mfma_f32_16x16x32_bf16 v[18:21], v[178:181], v[206:209], v[18:21]
	v_mfma_f32_16x16x32_bf16 v[6:9], v[170:173], v[214:217], v[6:9]
	v_mfma_f32_16x16x32_bf16 v[2:5], v[178:181], v[214:217], v[2:5]
	v_mfma_f32_16x16x32_bf16 v[54:57], v[174:177], v[190:193], v[54:57]
	v_mfma_f32_16x16x32_bf16 v[50:53], v[182:185], v[190:193], v[50:53]
	v_mfma_f32_16x16x32_bf16 v[38:41], v[174:177], v[202:205], v[38:41]
	v_mfma_f32_16x16x32_bf16 v[34:37], v[182:185], v[202:205], v[34:37]
	v_mfma_f32_16x16x32_bf16 v[22:25], v[174:177], v[210:213], v[22:25]
	v_mfma_f32_16x16x32_bf16 v[18:21], v[182:185], v[210:213], v[18:21]
	v_mfma_f32_16x16x32_bf16 v[6:9], v[174:177], v[218:221], v[6:9]
	v_mfma_f32_16x16x32_bf16 v[2:5], v[182:185], v[218:221], v[2:5]
	s_barrier
	s_setprio 0
	s_add_i32 s69, 0, 0x18000
	v_add_u32_e32 v153, s69, v148
	s_add_i32 s70, 0, 0x1c000
	ds_read_b128 v[154:157], v153
	ds_read_b128 v[158:161], v153 offset:1024
	ds_read_b128 v[162:165], v153 offset:2048
	ds_read_b128 v[166:169], v153 offset:3072
	v_add_u32_e32 v153, s70, v148
	ds_read_b128 v[170:173], v153
	ds_read_b128 v[174:177], v153 offset:1024
	ds_read_b128 v[178:181], v153 offset:2048
	ds_read_b128 v[182:185], v153 offset:3072
	s_add_u32 s46, s46, 0x100000
	s_addc_u32 s47, s47, 0
	s_mov_b32 m0, s51
	ds_read_b128 v[186:189], v152 offset:32768
	ds_read_b128 v[190:193], v152 offset:33792
	ds_read_b128 v[198:201], v152 offset:34816
	ds_read_b128 v[202:205], v152 offset:35840
	ds_read_b128 v[206:209], v152 offset:36864
	ds_read_b128 v[210:213], v152 offset:37888
	ds_read_b128 v[214:217], v152 offset:38912
	ds_read_b128 v[218:221], v152 offset:39936
	global_load_lds_dwordx4 v130, s[46:47]
	s_mov_b32 m0, s52
	s_nop 0
	global_load_lds_dwordx4 v134, s[46:47]
	s_waitcnt vmcnt(8)
	s_waitcnt lgkmcnt(0)
	.p2align	6
	s_setprio 1
	s_barrier
	v_mfma_f32_16x16x32_bf16 v[126:129], v[154:157], v[186:189], v[126:129]
	v_mfma_f32_16x16x32_bf16 v[122:125], v[162:165], v[186:189], v[122:125]
	v_mfma_f32_16x16x32_bf16 v[110:113], v[154:157], v[198:201], v[110:113]
	v_mfma_f32_16x16x32_bf16 v[106:109], v[162:165], v[198:201], v[106:109]
	v_mfma_f32_16x16x32_bf16 v[94:97], v[154:157], v[206:209], v[94:97]
	v_mfma_f32_16x16x32_bf16 v[90:93], v[162:165], v[206:209], v[90:93]
	v_mfma_f32_16x16x32_bf16 v[78:81], v[154:157], v[214:217], v[78:81]
	v_mfma_f32_16x16x32_bf16 v[74:77], v[162:165], v[214:217], v[74:77]
	v_mfma_f32_16x16x32_bf16 v[126:129], v[158:161], v[190:193], v[126:129]
	v_mfma_f32_16x16x32_bf16 v[122:125], v[166:169], v[190:193], v[122:125]
	v_mfma_f32_16x16x32_bf16 v[110:113], v[158:161], v[202:205], v[110:113]
	v_mfma_f32_16x16x32_bf16 v[106:109], v[166:169], v[202:205], v[106:109]
	v_mfma_f32_16x16x32_bf16 v[94:97], v[158:161], v[210:213], v[94:97]
	v_mfma_f32_16x16x32_bf16 v[90:93], v[166:169], v[210:213], v[90:93]
	v_mfma_f32_16x16x32_bf16 v[78:81], v[158:161], v[218:221], v[78:81]
	v_mfma_f32_16x16x32_bf16 v[74:77], v[166:169], v[218:221], v[74:77]
	v_mfma_f32_16x16x32_bf16 v[118:121], v[170:173], v[186:189], v[118:121]
	v_mfma_f32_16x16x32_bf16 v[114:117], v[178:181], v[186:189], v[114:117]
	v_mfma_f32_16x16x32_bf16 v[102:105], v[170:173], v[198:201], v[102:105]
	v_mfma_f32_16x16x32_bf16 v[98:101], v[178:181], v[198:201], v[98:101]
	v_mfma_f32_16x16x32_bf16 v[86:89], v[170:173], v[206:209], v[86:89]
	v_mfma_f32_16x16x32_bf16 v[82:85], v[178:181], v[206:209], v[82:85]
	v_mfma_f32_16x16x32_bf16 v[70:73], v[170:173], v[214:217], v[70:73]
	v_mfma_f32_16x16x32_bf16 v[66:69], v[178:181], v[214:217], v[66:69]
	v_mfma_f32_16x16x32_bf16 v[118:121], v[174:177], v[190:193], v[118:121]
	v_mfma_f32_16x16x32_bf16 v[114:117], v[182:185], v[190:193], v[114:117]
	v_mfma_f32_16x16x32_bf16 v[102:105], v[174:177], v[202:205], v[102:105]
	v_mfma_f32_16x16x32_bf16 v[98:101], v[182:185], v[202:205], v[98:101]
	v_mfma_f32_16x16x32_bf16 v[86:89], v[174:177], v[210:213], v[86:89]
	v_mfma_f32_16x16x32_bf16 v[82:85], v[182:185], v[210:213], v[82:85]
	v_mfma_f32_16x16x32_bf16 v[70:73], v[174:177], v[218:221], v[70:73]
	v_mfma_f32_16x16x32_bf16 v[66:69], v[182:185], v[218:221], v[66:69]
	s_barrier
	s_setprio 0
	s_add_u32 s44, s44, 0x80
	s_addc_u32 s45, s45, 0
	s_add_i32 m0, s33, 0x18000
	ds_read_b128 v[186:189], v152 offset:49152
	ds_read_b128 v[190:193], v152 offset:50176
	ds_read_b128 v[198:201], v152 offset:51200
	ds_read_b128 v[202:205], v152 offset:52224
	ds_read_b128 v[206:209], v152 offset:53248
	ds_read_b128 v[210:213], v152 offset:54272
	ds_read_b128 v[214:217], v152 offset:55296
	ds_read_b128 v[218:221], v152 offset:56320
	global_load_lds_dwordx4 v132, s[44:45]
	s_add_i32 m0, s33, 0x1a000
	s_add_u32 s46, s46, 0xfff00080
	global_load_lds_dwordx4 v136, s[44:45]
	s_addc_u32 s47, s47, -1
	s_add_u32 s44, s44, 0x100000
	s_addc_u32 s45, s45, 0
	s_add_i32 m0, s33, 0x1c000
	s_nop 0
	global_load_lds_dwordx4 v132, s[44:45]
	s_add_i32 m0, s33, 0x1e000
	s_nop 0
	global_load_lds_dwordx4 v136, s[44:45]
	s_mov_b32 m0, s55
	s_nop 0
	global_load_lds_dwordx4 v130, s[46:47]
	s_mov_b32 m0, s56
	s_nop 0
	global_load_lds_dwordx4 v134, s[46:47]
	s_waitcnt vmcnt(8)
	s_waitcnt lgkmcnt(0)
	.p2align	6
	s_setprio 1
	s_barrier
	v_mfma_f32_16x16x32_bf16 v[62:65], v[154:157], v[186:189], v[62:65]
	v_mfma_f32_16x16x32_bf16 v[58:61], v[162:165], v[186:189], v[58:61]
	v_mfma_f32_16x16x32_bf16 v[46:49], v[154:157], v[198:201], v[46:49]
	v_mfma_f32_16x16x32_bf16 v[42:45], v[162:165], v[198:201], v[42:45]
	v_mfma_f32_16x16x32_bf16 v[30:33], v[154:157], v[206:209], v[30:33]
	v_mfma_f32_16x16x32_bf16 v[26:29], v[162:165], v[206:209], v[26:29]
	v_mfma_f32_16x16x32_bf16 v[14:17], v[154:157], v[214:217], v[14:17]
	v_mfma_f32_16x16x32_bf16 v[10:13], v[162:165], v[214:217], v[10:13]
	v_mfma_f32_16x16x32_bf16 v[62:65], v[158:161], v[190:193], v[62:65]
	v_mfma_f32_16x16x32_bf16 v[58:61], v[166:169], v[190:193], v[58:61]
	v_mfma_f32_16x16x32_bf16 v[46:49], v[158:161], v[202:205], v[46:49]
	v_mfma_f32_16x16x32_bf16 v[42:45], v[166:169], v[202:205], v[42:45]
	v_mfma_f32_16x16x32_bf16 v[30:33], v[158:161], v[210:213], v[30:33]
	v_mfma_f32_16x16x32_bf16 v[26:29], v[166:169], v[210:213], v[26:29]
	v_mfma_f32_16x16x32_bf16 v[14:17], v[158:161], v[218:221], v[14:17]
	v_mfma_f32_16x16x32_bf16 v[10:13], v[166:169], v[218:221], v[10:13]
	v_mfma_f32_16x16x32_bf16 v[54:57], v[170:173], v[186:189], v[54:57]
	v_mfma_f32_16x16x32_bf16 v[50:53], v[178:181], v[186:189], v[50:53]
	v_mfma_f32_16x16x32_bf16 v[38:41], v[170:173], v[198:201], v[38:41]
	v_mfma_f32_16x16x32_bf16 v[34:37], v[178:181], v[198:201], v[34:37]
	v_mfma_f32_16x16x32_bf16 v[22:25], v[170:173], v[206:209], v[22:25]
	v_mfma_f32_16x16x32_bf16 v[18:21], v[178:181], v[206:209], v[18:21]
	v_mfma_f32_16x16x32_bf16 v[6:9], v[170:173], v[214:217], v[6:9]
	v_mfma_f32_16x16x32_bf16 v[2:5], v[178:181], v[214:217], v[2:5]
	v_mfma_f32_16x16x32_bf16 v[54:57], v[174:177], v[190:193], v[54:57]
	v_mfma_f32_16x16x32_bf16 v[50:53], v[182:185], v[190:193], v[50:53]
	v_mfma_f32_16x16x32_bf16 v[38:41], v[174:177], v[202:205], v[38:41]
	v_mfma_f32_16x16x32_bf16 v[34:37], v[182:185], v[202:205], v[34:37]
	v_mfma_f32_16x16x32_bf16 v[22:25], v[174:177], v[210:213], v[22:25]
	v_mfma_f32_16x16x32_bf16 v[18:21], v[182:185], v[210:213], v[18:21]
	v_mfma_f32_16x16x32_bf16 v[6:9], v[174:177], v[218:221], v[6:9]
	v_mfma_f32_16x16x32_bf16 v[2:5], v[182:185], v[218:221], v[2:5]
	s_barrier
	s_setprio 0
	s_add_i32 s68, s68, 2
	s_add_u32 s42, s42, 0x100
	s_addc_u32 s43, s43, 0
	s_add_u32 s66, s66, 0x100
	s_addc_u32 s67, s67, 0
	s_cmp_gt_u32 s68, 61
	s_cbranch_scc0 .LBB0_807
	s_and_b64 vcc, exec, s[14:15]
	s_cbranch_vccz .LBB0_810
	s_barrier

.LBB0_897:
	ds_read_b128 v[146:149], v156
	ds_read_b128 v[150:153], v156 offset:1024
	ds_read_b128 v[160:163], v156 offset:2048
	ds_read_b128 v[164:167], v156 offset:3072
	ds_read_b128 v[168:171], v157
	ds_read_b128 v[172:175], v157 offset:1024
	ds_read_b128 v[176:179], v157 offset:2048
	ds_read_b128 v[180:183], v157 offset:3072
	s_add_u32 s44, s42, 0xffc00080
	s_addc_u32 s45, s43, -1
	s_cmpk_eq_i32 s67, 0xfc
	s_cselect_b32 s47, s35, s45
	s_cselect_b32 s46, s63, s44
	s_cselect_b32 s45, s31, s66
	s_cselect_b32 s44, s64, s65
	s_add_i32 m0, s41, 0xc000
	ds_read_b128 v[184:187], v158
	ds_read_b128 v[188:191], v158 offset:1024
	ds_read_b128 v[192:195], v158 offset:2048
	ds_read_b128 v[198:201], v158 offset:3072
	ds_read_b128 v[202:205], v158 offset:4096
	ds_read_b128 v[206:209], v158 offset:5120
	ds_read_b128 v[210:213], v158 offset:6144
	ds_read_b128 v[214:217], v158 offset:7168
	global_load_lds_dwordx4 v138, s[42:43]
	s_add_i32 m0, s41, 0xe000
	s_nop 0
	global_load_lds_dwordx4 v140, s[42:43]
	s_waitcnt vmcnt(8)
	s_waitcnt lgkmcnt(0)
	.p2align	6
	s_setprio 1
	s_barrier
	v_mfma_f32_16x16x32_bf16 v[126:129], v[146:149], v[184:187], v[126:129]
	v_mfma_f32_16x16x32_bf16 v[122:125], v[160:163], v[184:187], v[122:125]
	v_mfma_f32_16x16x32_bf16 v[110:113], v[146:149], v[192:195], v[110:113]
	v_mfma_f32_16x16x32_bf16 v[106:109], v[160:163], v[192:195], v[106:109]
	v_mfma_f32_16x16x32_bf16 v[94:97], v[146:149], v[202:205], v[94:97]
	v_mfma_f32_16x16x32_bf16 v[90:93], v[160:163], v[202:205], v[90:93]
	v_mfma_f32_16x16x32_bf16 v[78:81], v[146:149], v[210:213], v[78:81]
	v_mfma_f32_16x16x32_bf16 v[74:77], v[160:163], v[210:213], v[74:77]
	v_mfma_f32_16x16x32_bf16 v[126:129], v[150:153], v[188:191], v[126:129]
	v_mfma_f32_16x16x32_bf16 v[122:125], v[164:167], v[188:191], v[122:125]
	v_mfma_f32_16x16x32_bf16 v[110:113], v[150:153], v[198:201], v[110:113]
	v_mfma_f32_16x16x32_bf16 v[106:109], v[164:167], v[198:201], v[106:109]
	v_mfma_f32_16x16x32_bf16 v[94:97], v[150:153], v[206:209], v[94:97]
	v_mfma_f32_16x16x32_bf16 v[90:93], v[164:167], v[206:209], v[90:93]
	v_mfma_f32_16x16x32_bf16 v[78:81], v[150:153], v[214:217], v[78:81]
	v_mfma_f32_16x16x32_bf16 v[74:77], v[164:167], v[214:217], v[74:77]
	v_mfma_f32_16x16x32_bf16 v[118:121], v[168:171], v[184:187], v[118:121]
	v_mfma_f32_16x16x32_bf16 v[114:117], v[176:179], v[184:187], v[114:117]
	v_mfma_f32_16x16x32_bf16 v[102:105], v[168:171], v[192:195], v[102:105]
	v_mfma_f32_16x16x32_bf16 v[98:101], v[176:179], v[192:195], v[98:101]
	v_mfma_f32_16x16x32_bf16 v[86:89], v[168:171], v[202:205], v[86:89]
	v_mfma_f32_16x16x32_bf16 v[82:85], v[176:179], v[202:205], v[82:85]
	v_mfma_f32_16x16x32_bf16 v[70:73], v[168:171], v[210:213], v[70:73]
	v_mfma_f32_16x16x32_bf16 v[66:69], v[176:179], v[210:213], v[66:69]
	v_mfma_f32_16x16x32_bf16 v[118:121], v[172:175], v[188:191], v[118:121]
	v_mfma_f32_16x16x32_bf16 v[114:117], v[180:183], v[188:191], v[114:117]
	v_mfma_f32_16x16x32_bf16 v[102:105], v[172:175], v[198:201], v[102:105]
	v_mfma_f32_16x16x32_bf16 v[98:101], v[180:183], v[198:201], v[98:101]
	v_mfma_f32_16x16x32_bf16 v[86:89], v[172:175], v[206:209], v[86:89]
	v_mfma_f32_16x16x32_bf16 v[82:85], v[180:183], v[206:209], v[82:85]
	v_mfma_f32_16x16x32_bf16 v[70:73], v[172:175], v[214:217], v[70:73]
	v_mfma_f32_16x16x32_bf16 v[66:69], v[180:183], v[214:217], v[66:69]
	s_barrier
	s_setprio 0
	s_add_i32 s68, s56, s48
	s_mov_b32 m0, s68
	ds_read_b128 v[184:187], v158 offset:16384
	ds_read_b128 v[188:191], v158 offset:17408
	ds_read_b128 v[192:195], v158 offset:18432
	ds_read_b128 v[198:201], v158 offset:19456
	ds_read_b128 v[202:205], v158 offset:20480
	ds_read_b128 v[206:209], v158 offset:21504
	ds_read_b128 v[210:213], v158 offset:22528
	ds_read_b128 v[214:217], v158 offset:23552
	global_load_lds_dwordx4 v132, s[44:45]
	s_add_i32 m0, s68, 0x2000
	s_add_u32 s68, s44, 0x400000
	s_addc_u32 s69, s45, 0
	s_add_i32 s70, s57, s48
	global_load_lds_dwordx4 v136, s[44:45]
	s_mov_b32 m0, s70
	global_load_lds_dwordx4 v132, s[68:69]
	s_add_i32 m0, s70, 0x2000
	s_nop 0
	global_load_lds_dwordx4 v136, s[68:69]
	s_mov_b32 m0, s41
	s_nop 0
	global_load_lds_dwordx4 v130, s[46:47]
	s_mov_b32 m0, s49
	s_nop 0
	global_load_lds_dwordx4 v134, s[46:47]
	s_waitcnt vmcnt(8)
	s_waitcnt lgkmcnt(0)
	.p2align	6
	s_setprio 1
	s_barrier
	v_mfma_f32_16x16x32_bf16 v[62:65], v[146:149], v[184:187], v[62:65]
	v_mfma_f32_16x16x32_bf16 v[58:61], v[160:163], v[184:187], v[58:61]
	v_mfma_f32_16x16x32_bf16 v[46:49], v[146:149], v[192:195], v[46:49]
	v_mfma_f32_16x16x32_bf16 v[42:45], v[160:163], v[192:195], v[42:45]
	v_mfma_f32_16x16x32_bf16 v[30:33], v[146:149], v[202:205], v[30:33]
	v_mfma_f32_16x16x32_bf16 v[26:29], v[160:163], v[202:205], v[26:29]
	v_mfma_f32_16x16x32_bf16 v[14:17], v[146:149], v[210:213], v[14:17]
	v_mfma_f32_16x16x32_bf16 v[10:13], v[160:163], v[210:213], v[10:13]
	v_mfma_f32_16x16x32_bf16 v[62:65], v[150:153], v[188:191], v[62:65]
	v_mfma_f32_16x16x32_bf16 v[58:61], v[164:167], v[188:191], v[58:61]
	v_mfma_f32_16x16x32_bf16 v[46:49], v[150:153], v[198:201], v[46:49]
	v_mfma_f32_16x16x32_bf16 v[42:45], v[164:167], v[198:201], v[42:45]
	v_mfma_f32_16x16x32_bf16 v[30:33], v[150:153], v[206:209], v[30:33]
	v_mfma_f32_16x16x32_bf16 v[26:29], v[164:167], v[206:209], v[26:29]
	v_mfma_f32_16x16x32_bf16 v[14:17], v[150:153], v[214:217], v[14:17]
	v_mfma_f32_16x16x32_bf16 v[10:13], v[164:167], v[214:217], v[10:13]
	v_mfma_f32_16x16x32_bf16 v[54:57], v[168:171], v[184:187], v[54:57]
	v_mfma_f32_16x16x32_bf16 v[50:53], v[176:179], v[184:187], v[50:53]
	v_mfma_f32_16x16x32_bf16 v[38:41], v[168:171], v[192:195], v[38:41]
	v_mfma_f32_16x16x32_bf16 v[34:37], v[176:179], v[192:195], v[34:37]
	v_mfma_f32_16x16x32_bf16 v[22:25], v[168:171], v[202:205], v[22:25]
	v_mfma_f32_16x16x32_bf16 v[18:21], v[176:179], v[202:205], v[18:21]
	v_mfma_f32_16x16x32_bf16 v[6:9], v[168:171], v[210:213], v[6:9]
	v_mfma_f32_16x16x32_bf16 v[2:5], v[176:179], v[210:213], v[2:5]
	v_mfma_f32_16x16x32_bf16 v[54:57], v[172:175], v[188:191], v[54:57]
	v_mfma_f32_16x16x32_bf16 v[50:53], v[180:183], v[188:191], v[50:53]
	v_mfma_f32_16x16x32_bf16 v[38:41], v[172:175], v[198:201], v[38:41]
	v_mfma_f32_16x16x32_bf16 v[34:37], v[180:183], v[198:201], v[34:37]
	v_mfma_f32_16x16x32_bf16 v[22:25], v[172:175], v[206:209], v[22:25]
	v_mfma_f32_16x16x32_bf16 v[18:21], v[180:183], v[206:209], v[18:21]
	v_mfma_f32_16x16x32_bf16 v[6:9], v[172:175], v[214:217], v[6:9]
	v_mfma_f32_16x16x32_bf16 v[2:5], v[180:183], v[214:217], v[2:5]
	s_barrier
	s_setprio 0
	s_add_i32 s68, 0, 0x18000
	s_add_i32 s69, 0, 0x1c000
	v_add_u32_e32 v164, s68, v154
	v_add_u32_e32 v180, s69, v154
	ds_read_b128 v[146:149], v164
	ds_read_b128 v[150:153], v164 offset:1024
	ds_read_b128 v[160:163], v164 offset:2048
	ds_read_b128 v[164:167], v164 offset:3072
	ds_read_b128 v[168:171], v180
	ds_read_b128 v[172:175], v180 offset:1024
	ds_read_b128 v[176:179], v180 offset:2048
	ds_read_b128 v[180:183], v180 offset:3072
	s_add_u32 s46, s46, 0x400000
	s_addc_u32 s47, s47, 0
	s_mov_b32 m0, s50
	ds_read_b128 v[184:187], v158 offset:32768
	ds_read_b128 v[188:191], v158 offset:33792
	ds_read_b128 v[192:195], v158 offset:34816
	ds_read_b128 v[198:201], v158 offset:35840
	ds_read_b128 v[202:205], v158 offset:36864
	ds_read_b128 v[206:209], v158 offset:37888
	ds_read_b128 v[210:213], v158 offset:38912
	ds_read_b128 v[214:217], v158 offset:39936
	global_load_lds_dwordx4 v130, s[46:47]
	s_mov_b32 m0, s51
	s_nop 0
	global_load_lds_dwordx4 v134, s[46:47]
	s_waitcnt vmcnt(8)
	s_waitcnt lgkmcnt(0)
	.p2align	6
	s_setprio 1
	s_barrier
	v_mfma_f32_16x16x32_bf16 v[126:129], v[146:149], v[184:187], v[126:129]
	v_mfma_f32_16x16x32_bf16 v[122:125], v[160:163], v[184:187], v[122:125]
	v_mfma_f32_16x16x32_bf16 v[110:113], v[146:149], v[192:195], v[110:113]
	v_mfma_f32_16x16x32_bf16 v[106:109], v[160:163], v[192:195], v[106:109]
	v_mfma_f32_16x16x32_bf16 v[94:97], v[146:149], v[202:205], v[94:97]
	v_mfma_f32_16x16x32_bf16 v[90:93], v[160:163], v[202:205], v[90:93]
	v_mfma_f32_16x16x32_bf16 v[78:81], v[146:149], v[210:213], v[78:81]
	v_mfma_f32_16x16x32_bf16 v[74:77], v[160:163], v[210:213], v[74:77]
	v_mfma_f32_16x16x32_bf16 v[126:129], v[150:153], v[188:191], v[126:129]
	v_mfma_f32_16x16x32_bf16 v[122:125], v[164:167], v[188:191], v[122:125]
	v_mfma_f32_16x16x32_bf16 v[110:113], v[150:153], v[198:201], v[110:113]
	v_mfma_f32_16x16x32_bf16 v[106:109], v[164:167], v[198:201], v[106:109]
	v_mfma_f32_16x16x32_bf16 v[94:97], v[150:153], v[206:209], v[94:97]
	v_mfma_f32_16x16x32_bf16 v[90:93], v[164:167], v[206:209], v[90:93]
	v_mfma_f32_16x16x32_bf16 v[78:81], v[150:153], v[214:217], v[78:81]
	v_mfma_f32_16x16x32_bf16 v[74:77], v[164:167], v[214:217], v[74:77]
	v_mfma_f32_16x16x32_bf16 v[118:121], v[168:171], v[184:187], v[118:121]
	v_mfma_f32_16x16x32_bf16 v[114:117], v[176:179], v[184:187], v[114:117]
	v_mfma_f32_16x16x32_bf16 v[102:105], v[168:171], v[192:195], v[102:105]
	v_mfma_f32_16x16x32_bf16 v[98:101], v[176:179], v[192:195], v[98:101]
	v_mfma_f32_16x16x32_bf16 v[86:89], v[168:171], v[202:205], v[86:89]
	v_mfma_f32_16x16x32_bf16 v[82:85], v[176:179], v[202:205], v[82:85]
	v_mfma_f32_16x16x32_bf16 v[70:73], v[168:171], v[210:213], v[70:73]
	v_mfma_f32_16x16x32_bf16 v[66:69], v[176:179], v[210:213], v[66:69]
	v_mfma_f32_16x16x32_bf16 v[118:121], v[172:175], v[188:191], v[118:121]
	v_mfma_f32_16x16x32_bf16 v[114:117], v[180:183], v[188:191], v[114:117]
	v_mfma_f32_16x16x32_bf16 v[102:105], v[172:175], v[198:201], v[102:105]
	v_mfma_f32_16x16x32_bf16 v[98:101], v[180:183], v[198:201], v[98:101]
	v_mfma_f32_16x16x32_bf16 v[86:89], v[172:175], v[206:209], v[86:89]
	v_mfma_f32_16x16x32_bf16 v[82:85], v[180:183], v[206:209], v[82:85]
	v_mfma_f32_16x16x32_bf16 v[70:73], v[172:175], v[214:217], v[70:73]
	v_mfma_f32_16x16x32_bf16 v[66:69], v[180:183], v[214:217], v[66:69]
	s_barrier
	s_setprio 0
	s_add_u32 s44, s44, 0x80
	s_addc_u32 s45, s45, 0
	s_add_i32 m0, s48, 0x18000
	ds_read_b128 v[184:187], v158 offset:49152
	ds_read_b128 v[188:191], v158 offset:50176
	ds_read_b128 v[192:195], v158 offset:51200
	ds_read_b128 v[198:201], v158 offset:52224
	ds_read_b128 v[202:205], v158 offset:53248
	ds_read_b128 v[206:209], v158 offset:54272
	ds_read_b128 v[210:213], v158 offset:55296
	ds_read_b128 v[214:217], v158 offset:56320
	global_load_lds_dwordx4 v132, s[44:45]
	s_add_i32 m0, s48, 0x1a000
	s_add_u32 s46, s46, 0xffc00080
	global_load_lds_dwordx4 v136, s[44:45]
	s_addc_u32 s47, s47, -1
	s_add_u32 s44, s44, 0x400000
	s_addc_u32 s45, s45, 0
	s_add_i32 m0, s48, 0x1c000
	s_nop 0
	global_load_lds_dwordx4 v132, s[44:45]
	s_add_i32 m0, s48, 0x1e000
	s_nop 0
	global_load_lds_dwordx4 v136, s[44:45]
	s_mov_b32 m0, s53
	s_nop 0
	global_load_lds_dwordx4 v130, s[46:47]
	s_mov_b32 m0, s54
	s_nop 0
	global_load_lds_dwordx4 v134, s[46:47]
	s_waitcnt vmcnt(8)
	s_waitcnt lgkmcnt(0)
	.p2align	6
	s_setprio 1
	s_barrier
	v_mfma_f32_16x16x32_bf16 v[62:65], v[146:149], v[184:187], v[62:65]
	v_mfma_f32_16x16x32_bf16 v[58:61], v[160:163], v[184:187], v[58:61]
	v_mfma_f32_16x16x32_bf16 v[46:49], v[146:149], v[192:195], v[46:49]
	v_mfma_f32_16x16x32_bf16 v[42:45], v[160:163], v[192:195], v[42:45]
	v_mfma_f32_16x16x32_bf16 v[30:33], v[146:149], v[202:205], v[30:33]
	v_mfma_f32_16x16x32_bf16 v[26:29], v[160:163], v[202:205], v[26:29]
	v_mfma_f32_16x16x32_bf16 v[14:17], v[146:149], v[210:213], v[14:17]
	v_mfma_f32_16x16x32_bf16 v[10:13], v[160:163], v[210:213], v[10:13]
	v_mfma_f32_16x16x32_bf16 v[62:65], v[150:153], v[188:191], v[62:65]
	v_mfma_f32_16x16x32_bf16 v[58:61], v[164:167], v[188:191], v[58:61]
	v_mfma_f32_16x16x32_bf16 v[46:49], v[150:153], v[198:201], v[46:49]
	v_mfma_f32_16x16x32_bf16 v[42:45], v[164:167], v[198:201], v[42:45]
	v_mfma_f32_16x16x32_bf16 v[30:33], v[150:153], v[206:209], v[30:33]
	v_mfma_f32_16x16x32_bf16 v[26:29], v[164:167], v[206:209], v[26:29]
	v_mfma_f32_16x16x32_bf16 v[14:17], v[150:153], v[214:217], v[14:17]
	v_mfma_f32_16x16x32_bf16 v[10:13], v[164:167], v[214:217], v[10:13]
	v_mfma_f32_16x16x32_bf16 v[54:57], v[168:171], v[184:187], v[54:57]
	v_mfma_f32_16x16x32_bf16 v[50:53], v[176:179], v[184:187], v[50:53]
	v_mfma_f32_16x16x32_bf16 v[38:41], v[168:171], v[192:195], v[38:41]
	v_mfma_f32_16x16x32_bf16 v[34:37], v[176:179], v[192:195], v[34:37]
	v_mfma_f32_16x16x32_bf16 v[22:25], v[168:171], v[202:205], v[22:25]
	v_mfma_f32_16x16x32_bf16 v[18:21], v[176:179], v[202:205], v[18:21]
	v_mfma_f32_16x16x32_bf16 v[6:9], v[168:171], v[210:213], v[6:9]
	v_mfma_f32_16x16x32_bf16 v[2:5], v[176:179], v[210:213], v[2:5]
	v_mfma_f32_16x16x32_bf16 v[54:57], v[172:175], v[188:191], v[54:57]
	v_mfma_f32_16x16x32_bf16 v[50:53], v[180:183], v[188:191], v[50:53]
	v_mfma_f32_16x16x32_bf16 v[38:41], v[172:175], v[198:201], v[38:41]
	v_mfma_f32_16x16x32_bf16 v[34:37], v[180:183], v[198:201], v[34:37]
	v_mfma_f32_16x16x32_bf16 v[22:25], v[172:175], v[206:209], v[22:25]
	v_mfma_f32_16x16x32_bf16 v[18:21], v[180:183], v[206:209], v[18:21]
	v_mfma_f32_16x16x32_bf16 v[6:9], v[172:175], v[214:217], v[6:9]
	v_mfma_f32_16x16x32_bf16 v[2:5], v[180:183], v[214:217], v[2:5]
	s_barrier
	s_setprio 0
	s_add_i32 s67, s67, 2
	s_add_u32 s42, s42, 0x100
	s_addc_u32 s43, s43, 0
	s_add_u32 s65, s65, 0x100
	s_addc_u32 s66, s66, 0
	s_cmpk_gt_u32 s67, 0xfd
	s_cbranch_scc0 .LBB0_897
	s_and_b64 vcc, exec, s[14:15]
	s_cbranch_vccz .LBB0_900
	s_barrier
